# v41 + attention unit-top workgroup barrier removed (units alternate the starting LDS buffer)
# speedup vs baseline: 1.0019x; 1.0019x over previous
.LBB0_790:
	v_readfirstlane_b32 s100, v235
	s_nop 3
	s_mul_i32 s101, s100, s42
	s_sub_i32 s0, s42, 1
	s_sub_i32 s0, s0, s2
	s_bitcmp0_b32 s100, 0
	s_cselect_b32 s0, s2, s0
	s_add_i32 s101, s101, s0
	v_add_u32_e32 v235, 1, v235
	v_mov_b32_e32 v0, s101
	s_movk_i32 s0, 0x480
	s_mov_b64 s[8:9], -1
	v_cmp_gt_i32_e64 s[6:7], s0, v0
	s_and_saveexec_b64 s[68:69], s[6:7]
	s_cbranch_execz .LBB0_789
	v_ashrrev_i32_e32 v1, 31, v0
	v_lshrrev_b32_e32 v1, 25, v1
	v_add_u32_e32 v1, v0, v1
	v_ashrrev_i32_e32 v8, 7, v1
	v_and_b32_e32 v1, 0xffffff80, v1
	v_sub_u32_e32 v0, v0, v1
	v_mov_b32_e32 v1, 11
	v_lshrrev_b16_sdwa v1, v1, sext(v0) dst_sel:DWORD dst_unused:UNUSED_PAD src0_sel:DWORD src1_sel:BYTE_0
	v_and_b32_e32 v1, 15, v1
	v_add_u16_e32 v1, v0, v1
	v_sub_u32_e32 v9, 8, v8
	v_ashrrev_i16_sdwa v2, v198, sext(v1) dst_sel:DWORD dst_unused:UNUSED_PAD src0_sel:DWORD src1_sel:BYTE_0
	s_movk_i32 s0, 0x810
	v_and_b32_e32 v1, 0xf0, v1
	v_mul_hi_i32_i24_sdwa v135, sext(v2), s0 dst_sel:DWORD dst_unused:UNUSED_PAD src0_sel:WORD_0 src1_sel:DWORD
	v_mul_i32_i24_sdwa v134, sext(v2), s0 dst_sel:DWORD dst_unused:UNUSED_PAD src0_sel:WORD_0 src1_sel:DWORD
	v_mul_hi_i32_i24_e32 v3, 0x2040, v0
	v_mul_i32_i24_e32 v2, 0x2040, v0
	v_lshlrev_b32_e32 v10, 8, v9
	v_sub_u16_e32 v4, v0, v1
	v_lshl_add_u64 v[140:141], s[62:63], 0, v[2:3]
	v_add_u32_e32 v164, v10, v156
	v_mov_b32_e32 v2, 6
	v_lshlrev_b32_sdwa v138, v2, sext(v4) dst_sel:DWORD dst_unused:UNUSED_PAD src0_sel:DWORD src1_sel:BYTE_0
	v_max_i32_e32 v6, 0xf0, v164
	v_ashrrev_i32_e32 v139, 31, v138
	v_add_u32_e32 v172, 0xffffff10, v6
	v_lshlrev_b64 v[2:3], 1, v[138:139]
	v_lshl_add_u64 v[6:7], v[134:135], 0, v[172:173]
	v_lshl_add_u64 v[4:5], v[120:121], 0, v[2:3]
	v_lshlrev_b64 v[6:7], 12, v[6:7]
	v_lshl_add_u64 v[6:7], v[4:5], 0, v[6:7]
	v_or_b32_e32 v139, 16, v164
	global_load_dwordx4 v[20:23], v[6:7], off
	global_load_dwordx4 v[24:27], v[6:7], off offset:64
	v_max_i32_e32 v6, 0xf0, v139
	v_add_u32_e32 v172, 0xffffff10, v6
	v_lshl_add_u64 v[6:7], v[134:135], 0, v[172:173]
	v_lshlrev_b64 v[6:7], 12, v[6:7]
	v_ashrrev_i32_e32 v1, 31, v0
	v_lshl_add_u64 v[4:5], v[4:5], 0, v[6:7]
	global_load_dwordx4 v[28:31], v[4:5], off
	global_load_dwordx4 v[32:35], v[4:5], off offset:64
	v_lshl_add_u64 v[4:5], v[134:135], 0, v[124:125]
	v_lshlrev_b64 v[0:1], 6, v[0:1]
	v_lshlrev_b64 v[4:5], 11, v[4:5]
	v_lshl_add_u64 v[0:1], v[0:1], 0, v[122:123]
	v_mov_b64_e32 v[6:7], s[88:89]
	v_lshl_add_u64 v[4:5], s[70:71], 0, v[4:5]
	v_mad_u64_u32 v[144:145], s[6:7], v0, s52, v[6:7]
	v_lshl_add_u64 v[4:5], v[4:5], 0, v[2:3]
	v_lshlrev_b32_e32 v142, 1, v126
	v_mov_b32_e32 v143, v173
	v_mad_i32_i24 v145, v1, s52, v145
	v_mov_b32_e32 v131, v173
	v_lshlrev_b32_e32 v165, 2, v9
	v_lshl_add_u64 v[4:5], v[4:5], 0, v[142:143]
	v_lshl_add_u64 v[0:1], v[144:145], 0, v[130:131]
	v_mov_b32_e32 v133, v173
	v_or_b32_e32 v166, 3, v165
	global_load_dwordx4 v[36:39], v[4:5], off
	global_load_dwordx4 v[40:43], v[0:1], off offset:-96
	v_lshl_add_u64 v[0:1], v[140:141], 0, v[132:133]
	global_load_dword v131, v[0:1], off offset:-192
	v_min_u32_e32 v0, 4, v166
	v_lshl_add_u32 v6, v0, 6, v201
	v_add_u32_e32 v0, v6, v122
	v_max_i32_e32 v172, 0, v0
	v_lshl_add_u64 v[0:1], v[134:135], 0, v[172:173]
	v_lshlrev_b64 v[0:1], 11, v[0:1]
	v_lshl_add_u64 v[0:1], s[70:71], 0, v[0:1]
	v_add_u32_e32 v4, v6, v126
	v_lshl_add_u64 v[0:1], v[0:1], 0, v[2:3]
	v_max_i32_e32 v4, 0, v4
	v_lshl_add_u64 v[0:1], v[0:1], 0, v[142:143]
	v_lshlrev_b32_e32 v172, 1, v4
	v_lshl_add_u64 v[4:5], v[144:145], 0, v[172:173]
	global_load_dwordx4 v[44:47], v[0:1], off
	global_load_dwordx4 v[48:51], v[4:5], off
	v_add_u32_e32 v0, v6, v154
	v_max_i32_e32 v0, 0, v0
	v_lshlrev_b32_e32 v172, 2, v0
	v_lshl_add_u64 v[0:1], v[140:141], 0, v[172:173]
	global_load_dword v167, v[0:1], off
	v_min_u32_e32 v0, 5, v166
	v_lshl_add_u32 v6, v0, 6, v201
	v_add_u32_e32 v0, v6, v122
	v_max_i32_e32 v172, 0, v0
	v_lshl_add_u64 v[0:1], v[134:135], 0, v[172:173]
	v_lshlrev_b64 v[0:1], 11, v[0:1]
	v_lshl_add_u64 v[0:1], s[70:71], 0, v[0:1]
	v_add_u32_e32 v4, v6, v126
	v_lshl_add_u64 v[0:1], v[0:1], 0, v[2:3]
	v_max_i32_e32 v4, 0, v4
	v_lshl_add_u64 v[0:1], v[0:1], 0, v[142:143]
	v_lshlrev_b32_e32 v172, 1, v4
	v_lshl_add_u64 v[4:5], v[144:145], 0, v[172:173]
	global_load_dwordx4 v[52:55], v[0:1], off
	global_load_dwordx4 v[56:59], v[4:5], off
	v_add_u32_e32 v0, v6, v154
	v_max_i32_e32 v0, 0, v0
	v_lshlrev_b32_e32 v172, 2, v0
	v_lshl_add_u64 v[0:1], v[140:141], 0, v[172:173]
	global_load_dword v169, v[0:1], off
	v_sub_u32_e32 v0, 0, v8
	v_or_b32_e32 v1, v10, v155
	v_lshl_add_u64 v[146:147], v[128:129], 0, v[2:3]
	v_lshlrev_b32_e32 v0, 8, v0
	v_mov_b32_e32 v2, v173
	v_mov_b32_e32 v3, v173
	v_add_u32_e32 v133, s85, v1
	v_sub_u32_e32 v168, 0, v0
	v_mov_b32_e32 v172, v173
	v_mov_b32_e32 v0, v173
	v_mov_b32_e32 v1, v173
	v_mov_b64_e32 v[6:7], v[2:3]
	v_mov_b64_e32 v[10:11], v[2:3]
	v_mov_b64_e32 v[14:15], v[2:3]
	v_mov_b64_e32 v[18:19], v[2:3]
	v_mov_b64_e32 v[62:63], v[2:3]
	v_mov_b64_e32 v[66:67], v[2:3]
	v_mov_b64_e32 v[70:71], v[2:3]
	s_mov_b32 s60, s87
	s_mov_b32 s84, 0
	v_or_b32_e32 v143, 16, v133
	v_mov_b32_e32 v148, 0xff800000
	s_mov_b64 s[34:35], 0
	v_and_b32_e32 v170, 1, v235
	s_mov_b32 s87, 0
	v_mov_b64_e32 v[4:5], v[0:1]
	v_mov_b64_e32 v[8:9], v[0:1]
	v_mov_b64_e32 v[12:13], v[0:1]
	v_mov_b64_e32 v[16:17], v[0:1]
	v_mov_b64_e32 v[60:61], v[0:1]
	v_mov_b64_e32 v[64:65], v[0:1]
	v_mov_b64_e32 v[68:69], v[0:1]
	v_mov_b64_e32 v[136:137], v[172:173]
	v_mov_b32_e32 v149, 0xff800000
	v_min_u32_e32 v228, 5, v166
	v_lshl_add_u32 v234, v228, 6, v201
	v_add_u32_e32 v228, v234, v122
	v_add_u32_e32 v230, v234, v126
	v_max_i32_e32 v172, 0, v228
	v_max_i32_e32 v230, 0, v230
	v_lshl_add_u64 v[228:229], v[134:135], 0, v[172:173]
	v_lshlrev_b32_e32 v172, 1, v230
	v_add_u32_e32 v234, v234, v154
	v_lshlrev_b64 v[228:229], 11, v[228:229]
	v_lshl_add_u64 v[230:231], v[144:145], 0, v[172:173]
	v_max_i32_e32 v172, 0, v234
	v_lshl_add_u64 v[228:229], v[146:147], 0, v[228:229]
	v_lshl_add_u64 v[232:233], v[172:173], 2, v[140:141]
	v_mov_b32_e32 v172, v173
	s_branch .LBB0_798
